# P3 kv-up GEMM K-loop deep-pipelined too (on top of q-up)
# baseline (speedup 1.0000x reference)
.LBB0_604:
	v_lshl_add_u64 v[94:95], v[82:83], 0, s[6:7]
	v_lshl_add_u64 v[96:97], v[84:85], 0, s[4:5]
	v_lshl_add_u64 v[98:99], v[86:87], 0, s[4:5]
	v_lshl_add_u64 v[100:101], v[88:89], 0, s[4:5]
	s_mov_b64 s[66:67], 0x5b3c000
	v_lshl_add_u64 v[94:95], v[94:95], 0, s[66:67]
	s_nop 1
	v_readfirstlane_b32 s60, v94
	v_readfirstlane_b32 s61, v95
	v_readfirstlane_b32 s62, v96
	v_readfirstlane_b32 s63, v97
	v_readfirstlane_b32 s64, v102
	v_subrev_u32_e32 v186, s60, v94
	v_subrev_u32_e32 v190, s62, v96
	v_subrev_u32_e32 v191, s62, v98
	v_subrev_u32_e32 v192, s62, v100
	v_add_u32_e32 v187, 0x10800, v186
	v_add_u32_e32 v188, 0x21000, v186
	v_add_u32_e32 v189, 0x31800, v186
	v_add3_u32 v182, v109, v110, v111
	v_add_u32_e32 v183, v109, v112
	v_add_u32_e32 v185, v113, v112
	v_add3_u32 v184, v113, v110, v111
	s_add_u32 s60, s60, 0x80
	s_addc_u32 s61, s61, 0
	s_add_u32 m0, s64, 0x8000
	v_mov_b32_e32 v116, 0
	global_load_lds_dwordx4 v186, s[60:61]
	v_mov_b32_e32 v93, 0
	v_mov_b32_e32 v91, 0
	v_mov_b32_e32 v0, 0
	s_add_u32 m0, s64, 0x9000
	v_mov_b32_e32 v46, 0
	global_load_lds_dwordx4 v187, s[60:61]
	v_mov_b32_e32 v47, 0
	v_mov_b32_e32 v48, 0
	v_mov_b32_e32 v49, 0
	s_add_u32 m0, s64, 0xa000
	v_mov_b32_e32 v38, 0
	global_load_lds_dwordx4 v188, s[60:61]
	v_mov_b32_e32 v39, 0
	v_mov_b32_e32 v40, 0
	v_mov_b32_e32 v41, 0
	s_add_u32 m0, s64, 0xb000
	v_mov_b32_e32 v42, 0
	global_load_lds_dwordx4 v189, s[60:61]
	v_mov_b32_e32 v43, 0
	v_mov_b32_e32 v44, 0
	v_mov_b32_e32 v45, 0
	v_mov_b32_e32 v34, 0
	v_mov_b32_e32 v35, 0
	v_mov_b32_e32 v36, 0
	v_mov_b32_e32 v37, 0
	v_mov_b32_e32 v30, 0
	v_mov_b32_e32 v31, 0
	v_mov_b32_e32 v32, 0
	v_mov_b32_e32 v33, 0
	v_mov_b32_e32 v26, 0
	v_mov_b32_e32 v27, 0
	v_mov_b32_e32 v28, 0
	v_mov_b32_e32 v29, 0
	v_mov_b32_e32 v22, 0
	v_mov_b32_e32 v23, 0
	v_mov_b32_e32 v24, 0
	v_mov_b32_e32 v25, 0
	v_mov_b32_e32 v18, 0
	v_mov_b32_e32 v19, 0
	v_mov_b32_e32 v20, 0
	v_mov_b32_e32 v21, 0
	v_mov_b32_e32 v14, 0
	v_mov_b32_e32 v15, 0
	v_mov_b32_e32 v16, 0
	v_mov_b32_e32 v17, 0
	v_mov_b32_e32 v10, 0
	v_mov_b32_e32 v11, 0
	v_mov_b32_e32 v12, 0
	v_mov_b32_e32 v13, 0
	v_mov_b32_e32 v2, 0
	v_mov_b32_e32 v3, 0
	v_mov_b32_e32 v4, 0
	v_mov_b32_e32 v5, 0
	v_mov_b32_e32 v6, 0
	v_mov_b32_e32 v7, 0
	v_mov_b32_e32 v8, 0
	v_mov_b32_e32 v9, 0
	s_add_u32 s60, s60, 0x80
	s_addc_u32 s61, s61, 0
	s_waitcnt vmcnt(4) lgkmcnt(0)
	s_barrier
	ds_read_b128 v[126:129], v182 offset:0
	ds_read_b128 v[142:145], v183 offset:16384
	ds_read_b128 v[146:149], v183 offset:18432
	ds_read_b128 v[130:133], v182 offset:2048
	ds_read_b128 v[150:153], v183 offset:20480
	ds_read_b128 v[134:137], v182 offset:4096
	ds_read_b128 v[138:141], v182 offset:6144
	s_mov_b32 s65, 5

.LBB0_635:
	v_lshl_add_u64 v[120:121], v[102:103], 0, s[0:1]
	v_lshl_add_u64 v[122:123], v[104:105], 0, s[4:5]
	v_lshl_add_u64 v[124:125], v[106:107], 0, s[4:5]
	v_lshl_add_u64 v[126:127], v[108:109], 0, s[4:5]
	v_lshl_add_u64 v[128:129], v[110:111], 0, s[4:5]
	s_mov_b64 s[66:67], 0x5b3c600
	v_lshl_add_u64 v[120:121], v[120:121], 0, s[66:67]
	s_nop 1
	v_readfirstlane_b32 s60, v120
	v_readfirstlane_b32 s61, v121
	v_readfirstlane_b32 s62, v122
	v_readfirstlane_b32 s63, v123
	v_readfirstlane_b32 s64, v130
	v_subrev_u32_e32 v182, s60, v120
	v_subrev_u32_e32 v186, s62, v122
	v_subrev_u32_e32 v187, s62, v124
	v_subrev_u32_e32 v188, s62, v126
	v_subrev_u32_e32 v189, s62, v128
	v_add_u32_e32 v183, 0x10800, v182
	v_add_u32_e32 v184, 0x21000, v182
	v_add_u32_e32 v185, 0x31800, v182
	v_add3_u32 v178, v138, v139, v140
	v_add3_u32 v179, v138, v141, v140
	v_add3_u32 v181, v142, v141, v140
	v_add3_u32 v180, v142, v139, v140
	s_add_u32 s60, s60, 0x80
	s_addc_u32 s61, s61, 0
	s_add_u32 m0, s64, 0x8000
	v_mov_b32_e32 v117, 0
	global_load_lds_dwordx4 v182, s[60:61]
	v_mov_b32_e32 v115, 0
	v_mov_b32_e32 v113, 0
	v_mov_b32_e32 v0, 0
	s_add_u32 m0, s64, 0x9000
	v_mov_b32_e32 v2, 0
	global_load_lds_dwordx4 v183, s[60:61]
	v_mov_b32_e32 v3, 0
	v_mov_b32_e32 v4, 0
	v_mov_b32_e32 v5, 0
	s_add_u32 m0, s64, 0xa000
	v_mov_b32_e32 v6, 0
	global_load_lds_dwordx4 v184, s[60:61]
	v_mov_b32_e32 v7, 0
	v_mov_b32_e32 v8, 0
	v_mov_b32_e32 v9, 0
	s_add_u32 m0, s64, 0xb000
	v_mov_b32_e32 v10, 0
	global_load_lds_dwordx4 v185, s[60:61]
	v_mov_b32_e32 v11, 0
	v_mov_b32_e32 v12, 0
	v_mov_b32_e32 v13, 0
	v_mov_b32_e32 v14, 0
	v_mov_b32_e32 v15, 0
	v_mov_b32_e32 v16, 0
	v_mov_b32_e32 v17, 0
	v_mov_b32_e32 v18, 0
	v_mov_b32_e32 v19, 0
	v_mov_b32_e32 v20, 0
	v_mov_b32_e32 v21, 0
	v_mov_b32_e32 v26, 0
	v_mov_b32_e32 v27, 0
	v_mov_b32_e32 v28, 0
	v_mov_b32_e32 v29, 0
	v_mov_b32_e32 v34, 0
	v_mov_b32_e32 v35, 0
	v_mov_b32_e32 v36, 0
	v_mov_b32_e32 v37, 0
	v_mov_b32_e32 v38, 0
	v_mov_b32_e32 v39, 0
	v_mov_b32_e32 v40, 0
	v_mov_b32_e32 v41, 0
	v_mov_b32_e32 v42, 0
	v_mov_b32_e32 v43, 0
	v_mov_b32_e32 v44, 0
	v_mov_b32_e32 v45, 0
	v_mov_b32_e32 v46, 0
	v_mov_b32_e32 v47, 0
	v_mov_b32_e32 v48, 0
	v_mov_b32_e32 v49, 0
	v_mov_b32_e32 v50, 0
	v_mov_b32_e32 v51, 0
	v_mov_b32_e32 v52, 0
	v_mov_b32_e32 v53, 0
	v_mov_b32_e32 v58, 0
	v_mov_b32_e32 v59, 0
	v_mov_b32_e32 v60, 0
	v_mov_b32_e32 v61, 0
	v_mov_b32_e32 v62, 0
	v_mov_b32_e32 v63, 0
	v_mov_b32_e32 v64, 0
	v_mov_b32_e32 v65, 0
	v_mov_b32_e32 v54, 0
	v_mov_b32_e32 v55, 0
	v_mov_b32_e32 v56, 0
	v_mov_b32_e32 v57, 0
	v_mov_b32_e32 v30, 0
	v_mov_b32_e32 v31, 0
	v_mov_b32_e32 v32, 0
	v_mov_b32_e32 v33, 0
	v_mov_b32_e32 v22, 0
	v_mov_b32_e32 v23, 0
	v_mov_b32_e32 v24, 0
	v_mov_b32_e32 v25, 0
	s_add_u32 s60, s60, 0x80
	s_addc_u32 s61, s61, 0
	s_waitcnt vmcnt(4) lgkmcnt(0)
	s_barrier
	ds_read_b128 v[66:69], v178 offset:0
	ds_read_b128 v[82:85], v179 offset:16384
	ds_read_b128 v[86:89], v179 offset:18432
	ds_read_b128 v[70:73], v178 offset:2048
	ds_read_b128 v[90:93], v179 offset:20480
	ds_read_b128 v[94:97], v179 offset:22528
	ds_read_b128 v[74:77], v178 offset:4096
	ds_read_b128 v[78:81], v178 offset:6144
	s_mov_b32 s65, 1
.Lp3kv_loop:
	ds_read_b128 v[146:149], v180 offset:0
	ds_read_b128 v[162:165], v181 offset:16384
	ds_read_b128 v[166:169], v181 offset:18432
	ds_read_b128 v[150:153], v180 offset:2048
	ds_read_b128 v[170:173], v181 offset:20480
	ds_read_b128 v[174:177], v181 offset:22528
	ds_read_b128 v[154:157], v180 offset:4096
	ds_read_b128 v[158:161], v180 offset:6144
	s_waitcnt lgkmcnt(8)
	s_add_u32 m0, s64, 0xc000
	v_mfma_f32_16x16x32_bf16 v[2:5], v[66:69], v[82:85], v[2:5]
	v_dot2c_f32_bf16_e32 v117, v66, v66
	v_mfma_f32_16x16x32_bf16 v[6:9], v[66:69], v[86:89], v[6:9]
	v_dot2c_f32_bf16_e32 v115, v70, v70
	global_load_lds_dwordx4 v186, s[62:63]
	v_mfma_f32_16x16x32_bf16 v[10:13], v[66:69], v[90:93], v[10:13]
	v_dot2c_f32_bf16_e32 v113, v74, v74
	v_mfma_f32_16x16x32_bf16 v[14:17], v[66:69], v[94:97], v[14:17]
	v_dot2c_f32_bf16_e32 v0, v78, v78
	s_add_u32 m0, s64, 0xd000
	v_mfma_f32_16x16x32_bf16 v[18:21], v[70:73], v[82:85], v[18:21]
	v_dot2c_f32_bf16_e32 v117, v66, v66
	v_mfma_f32_16x16x32_bf16 v[26:29], v[70:73], v[86:89], v[26:29]
	v_dot2c_f32_bf16_e32 v115, v70, v70
	global_load_lds_dwordx4 v187, s[62:63]
	v_mfma_f32_16x16x32_bf16 v[34:37], v[70:73], v[90:93], v[34:37]
	v_dot2c_f32_bf16_e32 v113, v74, v74
	v_mfma_f32_16x16x32_bf16 v[38:41], v[70:73], v[94:97], v[38:41]
	v_dot2c_f32_bf16_e32 v0, v78, v78
	s_add_u32 m0, s64, 0xe000
	v_mfma_f32_16x16x32_bf16 v[42:45], v[74:77], v[82:85], v[42:45]
	v_dot2c_f32_bf16_e32 v117, v66, v66
	v_mfma_f32_16x16x32_bf16 v[46:49], v[74:77], v[86:89], v[46:49]
	v_dot2c_f32_bf16_e32 v115, v70, v70
	global_load_lds_dwordx4 v188, s[62:63]
	v_mfma_f32_16x16x32_bf16 v[50:53], v[74:77], v[90:93], v[50:53]
	v_dot2c_f32_bf16_e32 v113, v74, v74
	v_mfma_f32_16x16x32_bf16 v[58:61], v[74:77], v[94:97], v[58:61]
	v_dot2c_f32_bf16_e32 v0, v78, v78
	s_add_u32 m0, s64, 0xf000
	v_mfma_f32_16x16x32_bf16 v[62:65], v[78:81], v[82:85], v[62:65]
	v_dot2c_f32_bf16_e32 v117, v66, v66
	v_mfma_f32_16x16x32_bf16 v[54:57], v[78:81], v[86:89], v[54:57]
	v_dot2c_f32_bf16_e32 v115, v70, v70
	global_load_lds_dwordx4 v189, s[62:63]
	v_mfma_f32_16x16x32_bf16 v[30:33], v[78:81], v[90:93], v[30:33]
	v_dot2c_f32_bf16_e32 v113, v74, v74
	v_mfma_f32_16x16x32_bf16 v[22:25], v[78:81], v[94:97], v[22:25]
	v_dot2c_f32_bf16_e32 v0, v78, v78
	s_add_u32 s62, s62, 0x80
	s_addc_u32 s63, s63, 0
	s_waitcnt lgkmcnt(0)
	s_barrier
	s_add_u32 m0, s64, 0x0
	v_mfma_f32_16x16x32_bf16 v[2:5], v[146:149], v[162:165], v[2:5]
	v_dot2c_f32_bf16_e32 v117, v146, v146
	v_mfma_f32_16x16x32_bf16 v[6:9], v[146:149], v[166:169], v[6:9]
	v_dot2c_f32_bf16_e32 v115, v150, v150
	global_load_lds_dwordx4 v182, s[60:61]
	v_mfma_f32_16x16x32_bf16 v[10:13], v[146:149], v[170:173], v[10:13]
	v_dot2c_f32_bf16_e32 v113, v154, v154
	v_mfma_f32_16x16x32_bf16 v[14:17], v[146:149], v[174:177], v[14:17]
	v_dot2c_f32_bf16_e32 v0, v158, v158
	s_add_u32 m0, s64, 0x1000
	v_mfma_f32_16x16x32_bf16 v[18:21], v[150:153], v[162:165], v[18:21]
	v_dot2c_f32_bf16_e32 v117, v146, v146
	v_mfma_f32_16x16x32_bf16 v[26:29], v[150:153], v[166:169], v[26:29]
	v_dot2c_f32_bf16_e32 v115, v150, v150
	global_load_lds_dwordx4 v183, s[60:61]
	v_mfma_f32_16x16x32_bf16 v[34:37], v[150:153], v[170:173], v[34:37]
	v_dot2c_f32_bf16_e32 v113, v154, v154
	v_mfma_f32_16x16x32_bf16 v[38:41], v[150:153], v[174:177], v[38:41]
	v_dot2c_f32_bf16_e32 v0, v158, v158
	s_waitcnt vmcnt(2)
	s_barrier
	ds_read_b128 v[66:69], v178 offset:32768
	ds_read_b128 v[82:85], v179 offset:49152
	ds_read_b128 v[86:89], v179 offset:51200
	ds_read_b128 v[70:73], v178 offset:34816
	ds_read_b128 v[90:93], v179 offset:53248
	ds_read_b128 v[94:97], v179 offset:55296
	ds_read_b128 v[74:77], v178 offset:36864
	ds_read_b128 v[78:81], v178 offset:38912
	s_add_u32 m0, s64, 0x2000
	v_mfma_f32_16x16x32_bf16 v[42:45], v[154:157], v[162:165], v[42:45]
	v_dot2c_f32_bf16_e32 v117, v146, v146
	v_mfma_f32_16x16x32_bf16 v[46:49], v[154:157], v[166:169], v[46:49]
	v_dot2c_f32_bf16_e32 v115, v150, v150
	global_load_lds_dwordx4 v184, s[60:61]
	v_mfma_f32_16x16x32_bf16 v[50:53], v[154:157], v[170:173], v[50:53]
	v_dot2c_f32_bf16_e32 v113, v154, v154
	v_mfma_f32_16x16x32_bf16 v[58:61], v[154:157], v[174:177], v[58:61]
	v_dot2c_f32_bf16_e32 v0, v158, v158
	s_add_u32 m0, s64, 0x3000
	v_mfma_f32_16x16x32_bf16 v[62:65], v[158:161], v[162:165], v[62:65]
	v_dot2c_f32_bf16_e32 v117, v146, v146
	v_mfma_f32_16x16x32_bf16 v[54:57], v[158:161], v[166:169], v[54:57]
	v_dot2c_f32_bf16_e32 v115, v150, v150
	global_load_lds_dwordx4 v185, s[60:61]
	v_mfma_f32_16x16x32_bf16 v[30:33], v[158:161], v[170:173], v[30:33]
	v_dot2c_f32_bf16_e32 v113, v154, v154
	v_mfma_f32_16x16x32_bf16 v[22:25], v[158:161], v[174:177], v[22:25]
	v_dot2c_f32_bf16_e32 v0, v158, v158
	s_add_u32 s60, s60, 0x80
	s_addc_u32 s61, s61, 0
	ds_read_b128 v[146:149], v180 offset:32768
	ds_read_b128 v[162:165], v181 offset:49152
	ds_read_b128 v[166:169], v181 offset:51200
	ds_read_b128 v[150:153], v180 offset:34816
	ds_read_b128 v[170:173], v181 offset:53248
	ds_read_b128 v[174:177], v181 offset:55296
	ds_read_b128 v[154:157], v180 offset:36864
	ds_read_b128 v[158:161], v180 offset:38912
	s_waitcnt lgkmcnt(8)
	s_add_u32 m0, s64, 0x4000
	v_mfma_f32_16x16x32_bf16 v[2:5], v[66:69], v[82:85], v[2:5]
	v_dot2c_f32_bf16_e32 v117, v66, v66
	v_mfma_f32_16x16x32_bf16 v[6:9], v[66:69], v[86:89], v[6:9]
	v_dot2c_f32_bf16_e32 v115, v70, v70
	global_load_lds_dwordx4 v186, s[62:63]
	v_mfma_f32_16x16x32_bf16 v[10:13], v[66:69], v[90:93], v[10:13]
	v_dot2c_f32_bf16_e32 v113, v74, v74
	v_mfma_f32_16x16x32_bf16 v[14:17], v[66:69], v[94:97], v[14:17]
	v_dot2c_f32_bf16_e32 v0, v78, v78
	s_add_u32 m0, s64, 0x5000
	v_mfma_f32_16x16x32_bf16 v[18:21], v[70:73], v[82:85], v[18:21]
	v_dot2c_f32_bf16_e32 v117, v66, v66
	v_mfma_f32_16x16x32_bf16 v[26:29], v[70:73], v[86:89], v[26:29]
	v_dot2c_f32_bf16_e32 v115, v70, v70
	global_load_lds_dwordx4 v187, s[62:63]
	v_mfma_f32_16x16x32_bf16 v[34:37], v[70:73], v[90:93], v[34:37]
	v_dot2c_f32_bf16_e32 v113, v74, v74
	v_mfma_f32_16x16x32_bf16 v[38:41], v[70:73], v[94:97], v[38:41]
	v_dot2c_f32_bf16_e32 v0, v78, v78
	s_add_u32 m0, s64, 0x6000
	v_mfma_f32_16x16x32_bf16 v[42:45], v[74:77], v[82:85], v[42:45]
	v_dot2c_f32_bf16_e32 v117, v66, v66
	v_mfma_f32_16x16x32_bf16 v[46:49], v[74:77], v[86:89], v[46:49]
	v_dot2c_f32_bf16_e32 v115, v70, v70
	global_load_lds_dwordx4 v188, s[62:63]
	v_mfma_f32_16x16x32_bf16 v[50:53], v[74:77], v[90:93], v[50:53]
	v_dot2c_f32_bf16_e32 v113, v74, v74
	v_mfma_f32_16x16x32_bf16 v[58:61], v[74:77], v[94:97], v[58:61]
	v_dot2c_f32_bf16_e32 v0, v78, v78
	s_add_u32 m0, s64, 0x7000
	v_mfma_f32_16x16x32_bf16 v[62:65], v[78:81], v[82:85], v[62:65]
	v_dot2c_f32_bf16_e32 v117, v66, v66
	v_mfma_f32_16x16x32_bf16 v[54:57], v[78:81], v[86:89], v[54:57]
	v_dot2c_f32_bf16_e32 v115, v70, v70
	global_load_lds_dwordx4 v189, s[62:63]
	v_mfma_f32_16x16x32_bf16 v[30:33], v[78:81], v[90:93], v[30:33]
	v_dot2c_f32_bf16_e32 v113, v74, v74
	v_mfma_f32_16x16x32_bf16 v[22:25], v[78:81], v[94:97], v[22:25]
	v_dot2c_f32_bf16_e32 v0, v78, v78
	s_add_u32 s62, s62, 0x80
	s_addc_u32 s63, s63, 0
	s_waitcnt lgkmcnt(0)
	s_barrier
	s_add_u32 m0, s64, 0x8000
	v_mfma_f32_16x16x32_bf16 v[2:5], v[146:149], v[162:165], v[2:5]
	v_dot2c_f32_bf16_e32 v117, v146, v146
	v_mfma_f32_16x16x32_bf16 v[6:9], v[146:149], v[166:169], v[6:9]
	v_dot2c_f32_bf16_e32 v115, v150, v150
	global_load_lds_dwordx4 v182, s[60:61]
	v_mfma_f32_16x16x32_bf16 v[10:13], v[146:149], v[170:173], v[10:13]
	v_dot2c_f32_bf16_e32 v113, v154, v154
	v_mfma_f32_16x16x32_bf16 v[14:17], v[146:149], v[174:177], v[14:17]
	v_dot2c_f32_bf16_e32 v0, v158, v158
	s_add_u32 m0, s64, 0x9000
	v_mfma_f32_16x16x32_bf16 v[18:21], v[150:153], v[162:165], v[18:21]
	v_dot2c_f32_bf16_e32 v117, v146, v146
	v_mfma_f32_16x16x32_bf16 v[26:29], v[150:153], v[166:169], v[26:29]
	v_dot2c_f32_bf16_e32 v115, v150, v150
	global_load_lds_dwordx4 v183, s[60:61]
	v_mfma_f32_16x16x32_bf16 v[34:37], v[150:153], v[170:173], v[34:37]
	v_dot2c_f32_bf16_e32 v113, v154, v154
	v_mfma_f32_16x16x32_bf16 v[38:41], v[150:153], v[174:177], v[38:41]
	v_dot2c_f32_bf16_e32 v0, v158, v158
	s_waitcnt vmcnt(2)
	s_barrier
	ds_read_b128 v[66:69], v178 offset:0
	ds_read_b128 v[82:85], v179 offset:16384
	ds_read_b128 v[86:89], v179 offset:18432
	ds_read_b128 v[70:73], v178 offset:2048
	ds_read_b128 v[90:93], v179 offset:20480
	ds_read_b128 v[94:97], v179 offset:22528
	ds_read_b128 v[74:77], v178 offset:4096
	ds_read_b128 v[78:81], v178 offset:6144
	s_add_u32 m0, s64, 0xa000
	v_mfma_f32_16x16x32_bf16 v[42:45], v[154:157], v[162:165], v[42:45]
	v_dot2c_f32_bf16_e32 v117, v146, v146
	v_mfma_f32_16x16x32_bf16 v[46:49], v[154:157], v[166:169], v[46:49]
	v_dot2c_f32_bf16_e32 v115, v150, v150
	global_load_lds_dwordx4 v184, s[60:61]
	v_mfma_f32_16x16x32_bf16 v[50:53], v[154:157], v[170:173], v[50:53]
	v_dot2c_f32_bf16_e32 v113, v154, v154
	v_mfma_f32_16x16x32_bf16 v[58:61], v[154:157], v[174:177], v[58:61]
	v_dot2c_f32_bf16_e32 v0, v158, v158
	s_add_u32 m0, s64, 0xb000
	v_mfma_f32_16x16x32_bf16 v[62:65], v[158:161], v[162:165], v[62:65]
	v_dot2c_f32_bf16_e32 v117, v146, v146
	v_mfma_f32_16x16x32_bf16 v[54:57], v[158:161], v[166:169], v[54:57]
	v_dot2c_f32_bf16_e32 v115, v150, v150
	global_load_lds_dwordx4 v185, s[60:61]
	v_mfma_f32_16x16x32_bf16 v[30:33], v[158:161], v[170:173], v[30:33]
	v_dot2c_f32_bf16_e32 v113, v154, v154
	v_mfma_f32_16x16x32_bf16 v[22:25], v[158:161], v[174:177], v[22:25]
	v_dot2c_f32_bf16_e32 v0, v158, v158
	s_add_u32 s60, s60, 0x80
	s_addc_u32 s61, s61, 0
	s_sub_i32 s65, s65, 1
	s_cmp_lg_u32 s65, 0
	s_cbranch_scc1 .Lp3kv_loop
	ds_read_b128 v[146:149], v180 offset:0
	ds_read_b128 v[162:165], v181 offset:16384
	ds_read_b128 v[166:169], v181 offset:18432
	ds_read_b128 v[150:153], v180 offset:2048
	ds_read_b128 v[170:173], v181 offset:20480
	ds_read_b128 v[174:177], v181 offset:22528
	ds_read_b128 v[154:157], v180 offset:4096
	ds_read_b128 v[158:161], v180 offset:6144
	s_waitcnt lgkmcnt(8)
	s_add_u32 m0, s64, 0xc000
	v_mfma_f32_16x16x32_bf16 v[2:5], v[66:69], v[82:85], v[2:5]
	v_dot2c_f32_bf16_e32 v117, v66, v66
	v_mfma_f32_16x16x32_bf16 v[6:9], v[66:69], v[86:89], v[6:9]
	v_dot2c_f32_bf16_e32 v115, v70, v70
	global_load_lds_dwordx4 v186, s[62:63]
	v_mfma_f32_16x16x32_bf16 v[10:13], v[66:69], v[90:93], v[10:13]
	v_dot2c_f32_bf16_e32 v113, v74, v74
	v_mfma_f32_16x16x32_bf16 v[14:17], v[66:69], v[94:97], v[14:17]
	v_dot2c_f32_bf16_e32 v0, v78, v78
	s_add_u32 m0, s64, 0xd000
	v_mfma_f32_16x16x32_bf16 v[18:21], v[70:73], v[82:85], v[18:21]
	v_dot2c_f32_bf16_e32 v117, v66, v66
	v_mfma_f32_16x16x32_bf16 v[26:29], v[70:73], v[86:89], v[26:29]
	v_dot2c_f32_bf16_e32 v115, v70, v70
	global_load_lds_dwordx4 v187, s[62:63]
	v_mfma_f32_16x16x32_bf16 v[34:37], v[70:73], v[90:93], v[34:37]
	v_dot2c_f32_bf16_e32 v113, v74, v74
	v_mfma_f32_16x16x32_bf16 v[38:41], v[70:73], v[94:97], v[38:41]
	v_dot2c_f32_bf16_e32 v0, v78, v78
	s_add_u32 m0, s64, 0xe000
	v_mfma_f32_16x16x32_bf16 v[42:45], v[74:77], v[82:85], v[42:45]
	v_dot2c_f32_bf16_e32 v117, v66, v66
	v_mfma_f32_16x16x32_bf16 v[46:49], v[74:77], v[86:89], v[46:49]
	v_dot2c_f32_bf16_e32 v115, v70, v70
	global_load_lds_dwordx4 v188, s[62:63]
	v_mfma_f32_16x16x32_bf16 v[50:53], v[74:77], v[90:93], v[50:53]
	v_dot2c_f32_bf16_e32 v113, v74, v74
	v_mfma_f32_16x16x32_bf16 v[58:61], v[74:77], v[94:97], v[58:61]
	v_dot2c_f32_bf16_e32 v0, v78, v78
	s_add_u32 m0, s64, 0xf000
	v_mfma_f32_16x16x32_bf16 v[62:65], v[78:81], v[82:85], v[62:65]
	v_dot2c_f32_bf16_e32 v117, v66, v66
	v_mfma_f32_16x16x32_bf16 v[54:57], v[78:81], v[86:89], v[54:57]
	v_dot2c_f32_bf16_e32 v115, v70, v70
	global_load_lds_dwordx4 v189, s[62:63]
	v_mfma_f32_16x16x32_bf16 v[30:33], v[78:81], v[90:93], v[30:33]
	v_dot2c_f32_bf16_e32 v113, v74, v74
	v_mfma_f32_16x16x32_bf16 v[22:25], v[78:81], v[94:97], v[22:25]
	v_dot2c_f32_bf16_e32 v0, v78, v78
	s_add_u32 s62, s62, 0x80
	s_addc_u32 s63, s63, 0
	s_waitcnt lgkmcnt(0)
	s_barrier
	v_mfma_f32_16x16x32_bf16 v[2:5], v[146:149], v[162:165], v[2:5]
	v_dot2c_f32_bf16_e32 v117, v146, v146
	v_mfma_f32_16x16x32_bf16 v[6:9], v[146:149], v[166:169], v[6:9]
	v_dot2c_f32_bf16_e32 v115, v150, v150
	v_mfma_f32_16x16x32_bf16 v[10:13], v[146:149], v[170:173], v[10:13]
	v_dot2c_f32_bf16_e32 v113, v154, v154
	v_mfma_f32_16x16x32_bf16 v[14:17], v[146:149], v[174:177], v[14:17]
	v_dot2c_f32_bf16_e32 v0, v158, v158
	v_mfma_f32_16x16x32_bf16 v[18:21], v[150:153], v[162:165], v[18:21]
	v_dot2c_f32_bf16_e32 v117, v146, v146
	v_mfma_f32_16x16x32_bf16 v[26:29], v[150:153], v[166:169], v[26:29]
	v_dot2c_f32_bf16_e32 v115, v150, v150
	v_mfma_f32_16x16x32_bf16 v[34:37], v[150:153], v[170:173], v[34:37]
	v_dot2c_f32_bf16_e32 v113, v154, v154
	v_mfma_f32_16x16x32_bf16 v[38:41], v[150:153], v[174:177], v[38:41]
	v_dot2c_f32_bf16_e32 v0, v158, v158
	s_waitcnt vmcnt(0)
	s_barrier
	ds_read_b128 v[66:69], v178 offset:32768
	ds_read_b128 v[82:85], v179 offset:49152
	ds_read_b128 v[86:89], v179 offset:51200
	ds_read_b128 v[70:73], v178 offset:34816
	ds_read_b128 v[90:93], v179 offset:53248
	ds_read_b128 v[94:97], v179 offset:55296
	ds_read_b128 v[74:77], v178 offset:36864
	ds_read_b128 v[78:81], v178 offset:38912
	v_mfma_f32_16x16x32_bf16 v[42:45], v[154:157], v[162:165], v[42:45]
	v_dot2c_f32_bf16_e32 v117, v146, v146
	v_mfma_f32_16x16x32_bf16 v[46:49], v[154:157], v[166:169], v[46:49]
	v_dot2c_f32_bf16_e32 v115, v150, v150
	v_mfma_f32_16x16x32_bf16 v[50:53], v[154:157], v[170:173], v[50:53]
	v_dot2c_f32_bf16_e32 v113, v154, v154
	v_mfma_f32_16x16x32_bf16 v[58:61], v[154:157], v[174:177], v[58:61]
	v_dot2c_f32_bf16_e32 v0, v158, v158
	v_mfma_f32_16x16x32_bf16 v[62:65], v[158:161], v[162:165], v[62:65]
	v_dot2c_f32_bf16_e32 v117, v146, v146
	v_mfma_f32_16x16x32_bf16 v[54:57], v[158:161], v[166:169], v[54:57]
	v_dot2c_f32_bf16_e32 v115, v150, v150
	v_mfma_f32_16x16x32_bf16 v[30:33], v[158:161], v[170:173], v[30:33]
	v_dot2c_f32_bf16_e32 v113, v154, v154
	v_mfma_f32_16x16x32_bf16 v[22:25], v[158:161], v[174:177], v[22:25]
	v_dot2c_f32_bf16_e32 v0, v158, v158
	ds_read_b128 v[146:149], v180 offset:32768
	ds_read_b128 v[162:165], v181 offset:49152
	ds_read_b128 v[166:169], v181 offset:51200
	ds_read_b128 v[150:153], v180 offset:34816
	ds_read_b128 v[170:173], v181 offset:53248
	ds_read_b128 v[174:177], v181 offset:55296
	ds_read_b128 v[154:157], v180 offset:36864
	ds_read_b128 v[158:161], v180 offset:38912
	s_waitcnt lgkmcnt(8)
	v_mfma_f32_16x16x32_bf16 v[2:5], v[66:69], v[82:85], v[2:5]
	v_dot2c_f32_bf16_e32 v117, v66, v66
	v_mfma_f32_16x16x32_bf16 v[6:9], v[66:69], v[86:89], v[6:9]
	v_dot2c_f32_bf16_e32 v115, v70, v70
	v_mfma_f32_16x16x32_bf16 v[10:13], v[66:69], v[90:93], v[10:13]
	v_dot2c_f32_bf16_e32 v113, v74, v74
	v_mfma_f32_16x16x32_bf16 v[14:17], v[66:69], v[94:97], v[14:17]
	v_dot2c_f32_bf16_e32 v0, v78, v78
	v_mfma_f32_16x16x32_bf16 v[18:21], v[70:73], v[82:85], v[18:21]
	v_dot2c_f32_bf16_e32 v117, v66, v66
	v_mfma_f32_16x16x32_bf16 v[26:29], v[70:73], v[86:89], v[26:29]
	v_dot2c_f32_bf16_e32 v115, v70, v70
	v_mfma_f32_16x16x32_bf16 v[34:37], v[70:73], v[90:93], v[34:37]
	v_dot2c_f32_bf16_e32 v113, v74, v74
	v_mfma_f32_16x16x32_bf16 v[38:41], v[70:73], v[94:97], v[38:41]
	v_dot2c_f32_bf16_e32 v0, v78, v78
	v_mfma_f32_16x16x32_bf16 v[42:45], v[74:77], v[82:85], v[42:45]
	v_dot2c_f32_bf16_e32 v117, v66, v66
	v_mfma_f32_16x16x32_bf16 v[46:49], v[74:77], v[86:89], v[46:49]
	v_dot2c_f32_bf16_e32 v115, v70, v70
	v_mfma_f32_16x16x32_bf16 v[50:53], v[74:77], v[90:93], v[50:53]
	v_dot2c_f32_bf16_e32 v113, v74, v74
	v_mfma_f32_16x16x32_bf16 v[58:61], v[74:77], v[94:97], v[58:61]
	v_dot2c_f32_bf16_e32 v0, v78, v78
	v_mfma_f32_16x16x32_bf16 v[62:65], v[78:81], v[82:85], v[62:65]
	v_dot2c_f32_bf16_e32 v117, v66, v66
	v_mfma_f32_16x16x32_bf16 v[54:57], v[78:81], v[86:89], v[54:57]
	v_dot2c_f32_bf16_e32 v115, v70, v70
	v_mfma_f32_16x16x32_bf16 v[30:33], v[78:81], v[90:93], v[30:33]
	v_dot2c_f32_bf16_e32 v113, v74, v74
	v_mfma_f32_16x16x32_bf16 v[22:25], v[78:81], v[94:97], v[22:25]
	v_dot2c_f32_bf16_e32 v0, v78, v78
	s_waitcnt lgkmcnt(0)
	s_barrier
	v_mfma_f32_16x16x32_bf16 v[2:5], v[146:149], v[162:165], v[2:5]
	v_dot2c_f32_bf16_e32 v117, v146, v146
	v_mfma_f32_16x16x32_bf16 v[6:9], v[146:149], v[166:169], v[6:9]
	v_dot2c_f32_bf16_e32 v115, v150, v150
	v_mfma_f32_16x16x32_bf16 v[10:13], v[146:149], v[170:173], v[10:13]
	v_dot2c_f32_bf16_e32 v113, v154, v154
	v_mfma_f32_16x16x32_bf16 v[14:17], v[146:149], v[174:177], v[14:17]
	v_dot2c_f32_bf16_e32 v0, v158, v158
	v_mfma_f32_16x16x32_bf16 v[18:21], v[150:153], v[162:165], v[18:21]
	v_dot2c_f32_bf16_e32 v117, v146, v146
	v_mfma_f32_16x16x32_bf16 v[26:29], v[150:153], v[166:169], v[26:29]
	v_dot2c_f32_bf16_e32 v115, v150, v150
	v_mfma_f32_16x16x32_bf16 v[34:37], v[150:153], v[170:173], v[34:37]
	v_dot2c_f32_bf16_e32 v113, v154, v154
	v_mfma_f32_16x16x32_bf16 v[38:41], v[150:153], v[174:177], v[38:41]
	v_dot2c_f32_bf16_e32 v0, v158, v158
	v_mfma_f32_16x16x32_bf16 v[42:45], v[154:157], v[162:165], v[42:45]
	v_dot2c_f32_bf16_e32 v117, v146, v146
	v_mfma_f32_16x16x32_bf16 v[46:49], v[154:157], v[166:169], v[46:49]
	v_dot2c_f32_bf16_e32 v115, v150, v150
	v_mfma_f32_16x16x32_bf16 v[50:53], v[154:157], v[170:173], v[50:53]
	v_dot2c_f32_bf16_e32 v113, v154, v154
	v_mfma_f32_16x16x32_bf16 v[58:61], v[154:157], v[174:177], v[58:61]
	v_dot2c_f32_bf16_e32 v0, v158, v158
	v_mfma_f32_16x16x32_bf16 v[62:65], v[158:161], v[162:165], v[62:65]
	v_dot2c_f32_bf16_e32 v117, v146, v146
	v_mfma_f32_16x16x32_bf16 v[54:57], v[158:161], v[166:169], v[54:57]
	v_dot2c_f32_bf16_e32 v115, v150, v150
	v_mfma_f32_16x16x32_bf16 v[30:33], v[158:161], v[170:173], v[30:33]
	v_dot2c_f32_bf16_e32 v113, v154, v154
	v_mfma_f32_16x16x32_bf16 v[22:25], v[158:161], v[174:177], v[22:25]
	v_dot2c_f32_bf16_e32 v0, v158, v158
	s_nop 7
